# residual epilogues: first row group's residual-stream and gain loads issued before the row-exchange's closing barrier (only the LDS rstd read stays behind it)
# baseline (speedup 1.0000x reference)
; DI float bflo(unsigned u) { return __uint_as_float(u << 16); }
; DI float bfhi(unsigned u) { return __uint_as_float(u & 0xffff0000u); }
;     DI void operator()(pg8::f32x4 (&acc)[2][2][4][2], const pg8::Unit& u, int wr, int wc, int fr, int fq) const {
;     ...
;         const int colb = u.pn * 256 + wc * 32 + 8 * fq;
; #pragma unroll
;         for (int ai = 0; ai < 2; ++ai)
; #pragma unroll
;             for (int m = 0; m < 4; ++m) {
;                 const int rl = ai * 128 + wr * 64 + m * 16 + fr; const float r1 = S[rl];
;                 const size_t ro = (size_t)(u.pm * 256 + rl) * 1024 + colb;
;                 float q = 0.f;
; #pragma unroll
;                 for (int bj = 0; bj < 2; ++bj) {
;                     const v4u xw = *(const v4u*)(XB + ro + bj * 128);
;                     const v4f g0 = *(const v4f*)(gpost + colb + bj * 128), g1 = *(const v4f*)(gpost + colb + bj * 128 + 4);
;                     const pg8::f32x4 a0 = acc[ai][bj][m][0], a1 = acc[ai][bj][m][1];
;                     float v[8];
;                     v[0] = bflo(xw.x) + a0[0] * r1 * g0[0]; v[1] = bfhi(xw.x) + a0[1] * r1 * g0[1]; v[2] = bflo(xw.y) + a0[2] * r1 * g0[2]; v[3] = bfhi(xw.y) + a0[3] * r1 * g0[3];
;                     v[4] = bflo(xw.z) + a1[0] * r1 * g1[0]; v[5] = bfhi(xw.z) + a1[1] * r1 * g1[1]; v[6] = bflo(xw.w) + a1[2] * r1 * g1[2]; v[7] = bfhi(xw.w) + a1[3] * r1 * g1[3];
;                     q += ((v[0] * v[0] + v[1] * v[1]) + (v[2] * v[2] + v[3] * v[3])) + ((v[4] * v[4] + v[5] * v[5]) + (v[6] * v[6] + v[7] * v[7]));
.LBB0_132:
	s_or_b64 exec, exec, s[26:27]
	v_readlane_b32 s0, v255, 7
	v_readlane_b32 s1, v255, 8
	s_lshl_b64 s[22:23], s[0:1], 2
	s_add_u32 s26, s48, s22
	v_add_u32_e32 v134, v152, v158
	s_addc_u32 s27, s49, s23
	v_lshl_or_b32 v132, s8, 8, v160
	s_waitcnt lgkmcnt(0)
	v_ashrrev_i32_e32 v135, 31, v134
	s_add_u32 s22, s24, 0x7000000
	v_ashrrev_i32_e32 v133, 31, v132
	v_lshlrev_b64 v[136:137], 10, v[134:135]
	s_addc_u32 s23, s25, 0
	v_lshl_add_u64 v[150:151], v[136:137], 0, v[132:133]
	v_lshl_add_u64 v[136:137], v[150:151], 1, s[22:23]
	v_lshl_add_u64 v[130:131], v[132:133], 2, s[26:27]
	global_load_dwordx4 v[154:157], v[136:137], off
	global_load_dwordx4 v[206:209], v[136:137], off offset:256
	global_load_dwordx4 v[182:185], v[130:131], off offset:16
	global_load_dwordx4 v[186:189], v[130:131], off
	s_waitcnt lgkmcnt(0)
	s_barrier
	ds_read_b32 v148, v169
	s_mov_b64 s[26:27], -1
	s_and_b64 vcc, exec, s[18:19]
	s_waitcnt lgkmcnt(0)
	v_pk_mul_f32 v[128:129], v[128:129], v[148:149] op_sel_hi:[1,0]
	v_pk_mul_f32 v[122:123], v[122:123], v[148:149] op_sel_hi:[1,0]
	v_pk_mul_f32 v[126:127], v[126:127], v[148:149] op_sel_hi:[1,0]
	v_pk_mul_f32 v[124:125], v[124:125], v[148:149] op_sel_hi:[1,0]
	s_waitcnt vmcnt(0)
	v_lshlrev_b32_e32 v172, 16, v154
	v_and_b32_e32 v173, 0xffff0000, v154
	v_lshlrev_b32_e32 v154, 16, v155
	v_and_b32_e32 v155, 0xffff0000, v155
	v_pk_fma_f32 v[128:129], v[128:129], v[188:189], v[154:155]
	v_lshlrev_b32_e32 v154, 16, v156
	v_and_b32_e32 v155, 0xffff0000, v156
	v_pk_fma_f32 v[122:123], v[122:123], v[182:183], v[154:155]
	v_lshlrev_b32_e32 v154, 16, v157
	v_and_b32_e32 v155, 0xffff0000, v157
	v_pk_fma_f32 v[126:127], v[126:127], v[186:187], v[172:173]
	v_pk_fma_f32 v[124:125], v[124:125], v[184:185], v[154:155]
	s_cbranch_vccz .LBB0_134
	v_cvt_pk_bf16_f32 v154, v126, v127
	v_cvt_pk_bf16_f32 v155, v128, v129
	v_cvt_pk_bf16_f32 v156, v122, v123
	v_cvt_pk_bf16_f32 v157, v124, v125
	global_store_dwordx4 v[136:137], v[154:157], off
	s_mov_b64 s[26:27], 0

; DI unsigned pk2(float lo, float hi) { f32x2_t v = {lo, hi}; bf16x2_t b = __builtin_convertvector(v, bf16x2_t); return __builtin_bit_cast(unsigned, b); }
; DI float bflo(unsigned u) { return __uint_as_float(u << 16); }
; DI float bfhi(unsigned u) { return __uint_as_float(u & 0xffff0000u); }
;     DI void operator()(pg8::f32x4 (&acc)[2][2][4][2], const pg8::Unit& u, int wr, int wc, int fr, int fq) const {
;     ...
;         const int colb = u.pn * 256 + wc * 32 + 8 * fq;
; #pragma unroll
;         for (int ai = 0; ai < 2; ++ai)
; #pragma unroll
;             for (int m = 0; m < 4; ++m) {
;                 const int rl = ai * 128 + wr * 64 + m * 16 + fr; const float r1 = S[rl];
;                 const size_t ro = (size_t)(u.pm * 256 + rl) * 1024 + colb;
;                 float q = 0.f;
; #pragma unroll
;                 for (int bj = 0; bj < 2; ++bj) {
;                     const v4u xw = *(const v4u*)(XB + ro + bj * 128);
;                     const v4f g0 = *(const v4f*)(gpost + colb + bj * 128), g1 = *(const v4f*)(gpost + colb + bj * 128 + 4);
;                     const pg8::f32x4 a0 = acc[ai][bj][m][0], a1 = acc[ai][bj][m][1];
;                     float v[8];
;                     v[0] = bflo(xw.x) + a0[0] * r1 * g0[0]; v[1] = bfhi(xw.x) + a0[1] * r1 * g0[1]; v[2] = bflo(xw.y) + a0[2] * r1 * g0[2]; v[3] = bfhi(xw.y) + a0[3] * r1 * g0[3];
;                     v[4] = bflo(xw.z) + a1[0] * r1 * g1[0]; v[5] = bfhi(xw.z) + a1[1] * r1 * g1[1]; v[6] = bflo(xw.w) + a1[2] * r1 * g1[2]; v[7] = bfhi(xw.w) + a1[3] * r1 * g1[3];
;                     q += ((v[0] * v[0] + v[1] * v[1]) + (v[2] * v[2] + v[3] * v[3])) + ((v[4] * v[4] + v[5] * v[5]) + (v[6] * v[6] + v[7] * v[7]));
;                     if (last) { *(v4f*)(OUT + ro + bj * 128) = (v4f){v[0], v[1], v[2], v[3]}; *(v4f*)(OUT + ro + bj * 128 + 4) = (v4f){v[4], v[5], v[6], v[7]}; }
;                     else { v4u w; w.x = pk2(v[0], v[1]); w.y = pk2(v[2], v[3]); w.z = pk2(v[4], v[5]); w.w = pk2(v[6], v[7]); *(v4u*)(XB + ro + bj * 128) = w; }
;                 }
;                 q += __shfl_xor(q, 16); q += __shfl_xor(q, 32);
;                 if (fq == 0) slots2[(size_t)(u.pm * 256 + rl) * 16 + u.pn * 4 + wc] = q;
.LBB0_426:
	s_or_b64 exec, exec, s[24:25]
	v_readlane_b32 s0, v255, 7
	v_lshl_or_b32 v0, s20, 8, v162
	v_readlane_b32 s1, v255, 8
	v_ashrrev_i32_e32 v1, 31, v0
	v_add_u32_e32 v4, v150, v160
	s_lshl_b64 s[22:23], s[0:1], 2
	v_lshl_add_u64 v[2:3], v[0:1], 1, s[26:27]
	s_mov_b64 s[24:25], 0x7000000
	v_ashrrev_i32_e32 v5, 31, v4
	s_add_u32 s22, s28, s22
	v_lshl_add_u64 v[2:3], v[2:3], 0, s[24:25]
	v_lshlrev_b64 v[6:7], 11, v[4:5]
	s_addc_u32 s23, s29, s23
	v_lshl_add_u64 v[6:7], v[2:3], 0, v[6:7]
	v_lshl_add_u64 v[0:1], v[0:1], 2, s[22:23]
	global_load_dwordx4 v[152:155], v[6:7], off
	global_load_dwordx4 v[206:209], v[6:7], off offset:256
	global_load_dwordx4 v[156:159], v[0:1], off offset:16
	global_load_dwordx4 v[180:183], v[0:1], off
	s_waitcnt lgkmcnt(0)
	s_barrier
	ds_read_b32 v64, v174
	s_lshl_b32 s20, s20, 2
	s_ashr_i32 s21, s20, 31
	s_lshl_b64 s[20:21], s[20:21], 2
	s_waitcnt lgkmcnt(0)
	v_pk_mul_f32 v[148:149], v[148:149], v[64:65] op_sel_hi:[1,0]
	v_pk_mul_f32 v[144:145], v[144:145], v[64:65] op_sel_hi:[1,0]
	v_pk_mul_f32 v[146:147], v[146:147], v[64:65] op_sel_hi:[1,0]
	v_pk_mul_f32 v[130:131], v[130:131], v[64:65] op_sel_hi:[1,0]
	v_pk_mul_f32 v[126:127], v[126:127], v[64:65] op_sel_hi:[1,0]
	v_pk_mul_f32 v[124:125], v[124:125], v[64:65] op_sel_hi:[1,0]
	v_pk_mul_f32 v[122:123], v[122:123], v[64:65] op_sel_hi:[1,0]
	v_pk_mul_f32 v[128:129], v[128:129], v[64:65] op_sel_hi:[1,0]
	s_add_u32 s8, s26, s20
	s_addc_u32 s10, s27, s21
	s_add_u32 s8, s8, s50
	s_addc_u32 s10, s10, 0
	s_add_u32 s20, s8, 0x1c900000
	s_addc_u32 s21, s10, 0
	s_waitcnt vmcnt(0)
	v_lshlrev_b32_e32 v172, 16, v152
	v_and_b32_e32 v173, 0xffff0000, v152
	v_pk_fma_f32 v[172:173], v[148:149], v[180:181], v[172:173]
	v_lshlrev_b32_e32 v148, 16, v153
	v_and_b32_e32 v149, 0xffff0000, v153
	v_pk_fma_f32 v[180:181], v[144:145], v[182:183], v[148:149]
	v_lshlrev_b32_e32 v144, 16, v154
	v_and_b32_e32 v145, 0xffff0000, v154
	v_pk_fma_f32 v[156:157], v[146:147], v[156:157], v[144:145]
	v_lshlrev_b32_e32 v144, 16, v155
	v_and_b32_e32 v145, 0xffff0000, v155
	v_pk_fma_f32 v[158:159], v[130:131], v[158:159], v[144:145]
	v_cvt_pk_bf16_f32 v152, v172, v173
	v_cvt_pk_bf16_f32 v153, v180, v181
	v_cvt_pk_bf16_f32 v154, v156, v157
	v_cvt_pk_bf16_f32 v155, v158, v159
	global_store_dwordx4 v[6:7], v[152:155], off
	v_pk_mul_f32 v[144:145], v[180:181], v[180:181]
	v_pk_mul_f32 v[146:147], v[156:157], v[156:157]
	v_pk_mul_f32 v[148:149], v[158:159], v[158:159]
	global_load_dwordx4 v[156:159], v[0:1], off offset:528
	global_load_dwordx4 v[180:183], v[0:1], off offset:512
	v_pk_mul_f32 v[130:131], v[172:173], v[172:173]
	v_add_f32_e32 v64, v148, v149
	v_add_f32_e32 v146, v146, v147
	v_add_f32_e32 v144, v144, v145
	v_add_f32_e32 v130, v130, v131
	v_add_f32_e32 v64, v146, v64
	v_add_f32_e32 v130, v130, v144
	v_add_f32_e32 v64, v130, v64
	s_waitcnt vmcnt(2)
	v_lshlrev_b32_e32 v172, 16, v206
	v_and_b32_e32 v173, 0xffff0000, v206
	v_lshlrev_b32_e32 v152, 16, v207
	v_and_b32_e32 v153, 0xffff0000, v207
	s_waitcnt vmcnt(0)
	v_pk_fma_f32 v[126:127], v[126:127], v[182:183], v[152:153]
	v_lshlrev_b32_e32 v152, 16, v208
	v_and_b32_e32 v153, 0xffff0000, v208
	v_pk_fma_f32 v[124:125], v[124:125], v[156:157], v[152:153]
	v_lshlrev_b32_e32 v152, 16, v209
	v_and_b32_e32 v153, 0xffff0000, v209
	v_pk_fma_f32 v[152:153], v[122:123], v[158:159], v[152:153]
	v_pk_fma_f32 v[128:129], v[128:129], v[180:181], v[172:173]
	v_pk_mul_f32 v[156:157], v[124:125], v[124:125]
	v_pk_mul_f32 v[158:159], v[152:153], v[152:153]
	v_pk_mul_f32 v[122:123], v[128:129], v[128:129]
	v_pk_mul_f32 v[154:155], v[126:127], v[126:127]
	v_add_f32_e32 v130, v158, v159
	v_add_f32_e32 v131, v156, v157
	v_add_f32_e32 v130, v131, v130
	v_add_f32_e32 v131, v154, v155
	v_add_f32_e32 v122, v122, v123
	v_add_f32_e32 v122, v122, v131
	v_add_f32_e32 v122, v122, v130
	v_add_f32_e32 v64, v64, v122
	v_cvt_pk_bf16_f32 v122, v128, v129
	v_cvt_pk_bf16_f32 v123, v126, v127
	v_cvt_pk_bf16_f32 v124, v124, v125
	v_cvt_pk_bf16_f32 v125, v152, v153
	global_store_dwordx4 v[6:7], v[122:125], off offset:256
	ds_bpermute_b32 v6, v177, v64
	s_waitcnt lgkmcnt(0)
	v_add_f32_e32 v6, v64, v6
	ds_bpermute_b32 v7, v178, v6
	s_and_saveexec_b64 s[22:23], s[38:39]
	s_cbranch_execz .LBB0_428
	v_lshlrev_b64 v[4:5], 6, v[4:5]
	v_lshl_add_u64 v[4:5], s[20:21], 0, v[4:5]
	s_waitcnt lgkmcnt(0)
	v_add_f32_e32 v6, v6, v7
	global_store_dword v[4:5], v6, off
